# long-conv MFMA groups: next group's two B fragments prefetched into a second register set before this group's MFMAs
# speedup vs baseline: 1.0046x; 1.0026x over previous
; #define MFMA(a, b, c) __builtin_amdgcn_mfma_f32_32x32x16_bf16((a), (b), (c), 0, 0, 0)
; __device__ __forceinline__ void toeplitz_item(const Params& p, int layer, int half, int c, bf16* sm, int dry, unsigned* done_ctr) {
;     ...
;       for (int ni = 0; ni < 2; ++ni) {
;         const int nlo = 32 * wn + 64 * ni;
;         actv[ni] = half ? true : !((nlo + 31 - D < 0) || (nlo - D >= 128));
;         const int n = nlo + r;
;         const int src = n - D;
;         const bool valid = half ? ((unsigned)((n & 15) - D) < 16u) : ((unsigned)src < 128u);
;         bblk[ni] = valid ? src : 128;
;       }
;       if (!actv[0] && !actv[1]) continue;
;       const int tb = 16 * (3 - Dl) + 16 + hh - rt;
;       const bf16* ap0 = sW + (aq * 83 + tb - 4 * (2 * wm)) * 8;
;       const bf16* bp0 = sU + bblk[0] * 136 + 8 * hh;
;       const bf16* bp1 = sU + bblk[1] * 136 + 8 * hh;
;       if (actv[0] && actv[1]) {
; #pragma unroll
;         for (int ks = 0; ks < 8; ++ks) {
;           const s8v a0 = *(const s8v*)(ap0 + 16 * ks), a1 = *(const s8v*)(ap0 - 32 + 16 * ks);
;           const s8v b0 = *(const s8v*)(bp0 + 16 * ks), b1 = *(const s8v*)(bp1 + 16 * ks);
;           acc[0][0] = MFMA(a0, b0, acc[0][0]);
;           acc[1][0] = MFMA(a1, b0, acc[1][0]);
;           acc[0][1] = MFMA(a0, b1, acc[0][1]);
;           acc[1][1] = MFMA(a1, b1, acc[1][1]);
;         }
.LBB0_1147:
	s_or_b64 exec, exec, s[2:3]
	v_add_u32_e32 v66, 3, v123
	v_add_u32_e32 v124, s74, v122
	v_cmp_gt_u32_e64 s[2:3], 16, v66
	v_add_u32_e32 v66, 0x1100, v124
	ds_read_b128 v[70:73], v89 offset:35088
	v_cndmask_b32_e64 v66, v228, v66, s[2:3]
	v_add_u32_e32 v125, v90, v66
	ds_read_b128 v[66:69], v89 offset:35024
	ds_read_b128 v[74:77], v125
	v_add_u32_e32 v78, 0x5500, v124
	s_waitcnt lgkmcnt(0)
	v_mfma_f32_32x32x16_bf16 v[50:65], v[70:73], v[74:77], v[50:65]
	s_addk_i32 s74, 0xfbc0
	s_cmpk_eq_i32 s74, 0xe240
	v_mfma_f32_32x32x16_bf16 v[18:33], v[66:69], v[74:77], v[18:33]
	v_cndmask_b32_e64 v74, v228, v78, s[2:3]
	v_add_u32_e32 v134, v90, v74
	ds_read_b128 v[74:77], v134
	ds_read_b128 v[78:81], v89 offset:35120
	ds_read_b128 v[126:129], v125 offset:32
	s_waitcnt lgkmcnt(2)
	v_mfma_f32_32x32x16_bf16 v[34:49], v[70:73], v[74:77], v[34:49]
	v_mfma_f32_32x32x16_bf16 v[2:17], v[66:69], v[74:77], v[2:17]
	ds_read_b128 v[74:77], v89 offset:35056
	s_waitcnt lgkmcnt(1)
	v_mfma_f32_32x32x16_bf16 v[50:65], v[78:81], v[126:129], v[50:65]
	s_waitcnt lgkmcnt(0)
	v_mfma_f32_32x32x16_bf16 v[18:33], v[74:77], v[126:129], v[18:33]
	ds_read_b128 v[126:129], v134 offset:32
	s_waitcnt lgkmcnt(0)
	v_mfma_f32_32x32x16_bf16 v[34:49], v[78:81], v[126:129], v[34:49]
	v_mfma_f32_32x32x16_bf16 v[2:17], v[74:77], v[126:129], v[2:17]
	ds_read_b128 v[130:133], v125 offset:64
	ds_read_b128 v[200:203], v134 offset:64
	ds_read_b128 v[126:129], v89 offset:35152
	ds_read_b128 v[204:207], v125 offset:96
	ds_read_b128 v[208:211], v134 offset:96
	s_waitcnt lgkmcnt(4)
	v_mfma_f32_32x32x16_bf16 v[18:33], v[70:73], v[130:133], v[18:33]
	s_waitcnt lgkmcnt(3)
	v_mfma_f32_32x32x16_bf16 v[2:17], v[70:73], v[200:203], v[2:17]
	s_waitcnt lgkmcnt(2)
	v_mfma_f32_32x32x16_bf16 v[50:65], v[126:129], v[130:133], v[50:65]
	v_mfma_f32_32x32x16_bf16 v[34:49], v[126:129], v[200:203], v[34:49]
	ds_read_b128 v[70:73], v89 offset:35184
	ds_read_b128 v[130:133], v125 offset:128
	ds_read_b128 v[200:203], v134 offset:128
	s_waitcnt lgkmcnt(4)
	v_mfma_f32_32x32x16_bf16 v[18:33], v[78:81], v[204:207], v[18:33]
	s_waitcnt lgkmcnt(3)
	v_mfma_f32_32x32x16_bf16 v[2:17], v[78:81], v[208:211], v[2:17]
	s_waitcnt lgkmcnt(2)
	v_mfma_f32_32x32x16_bf16 v[50:65], v[70:73], v[204:207], v[50:65]
	v_mfma_f32_32x32x16_bf16 v[34:49], v[70:73], v[208:211], v[34:49]
	ds_read_b128 v[78:81], v89 offset:35216
	ds_read_b128 v[204:207], v125 offset:160
	ds_read_b128 v[208:211], v134 offset:160
	s_waitcnt lgkmcnt(4)
	v_mfma_f32_32x32x16_bf16 v[18:33], v[126:129], v[130:133], v[18:33]
	s_waitcnt lgkmcnt(3)
	v_mfma_f32_32x32x16_bf16 v[2:17], v[126:129], v[200:203], v[2:17]
	s_waitcnt lgkmcnt(2)
	v_mfma_f32_32x32x16_bf16 v[50:65], v[78:81], v[130:133], v[50:65]
	v_mfma_f32_32x32x16_bf16 v[34:49], v[78:81], v[200:203], v[34:49]
	ds_read_b128 v[126:129], v89 offset:35248
	ds_read_b128 v[130:133], v125 offset:192
	ds_read_b128 v[200:203], v134 offset:192
	s_waitcnt lgkmcnt(4)
	v_mfma_f32_32x32x16_bf16 v[18:33], v[70:73], v[204:207], v[18:33]
	s_waitcnt lgkmcnt(3)
	v_mfma_f32_32x32x16_bf16 v[2:17], v[70:73], v[208:211], v[2:17]
	s_waitcnt lgkmcnt(2)
	v_mfma_f32_32x32x16_bf16 v[50:65], v[126:129], v[204:207], v[50:65]
	v_mfma_f32_32x32x16_bf16 v[34:49], v[126:129], v[208:211], v[34:49]
	ds_read_b128 v[70:73], v89 offset:35280
	s_waitcnt lgkmcnt(2)
	v_mfma_f32_32x32x16_bf16 v[18:33], v[78:81], v[130:133], v[18:33]
	s_waitcnt lgkmcnt(1)
	v_mfma_f32_32x32x16_bf16 v[2:17], v[78:81], v[200:203], v[2:17]
	s_waitcnt lgkmcnt(0)
	v_mfma_f32_32x32x16_bf16 v[50:65], v[70:73], v[130:133], v[50:65]
	v_mfma_f32_32x32x16_bf16 v[34:49], v[70:73], v[200:203], v[34:49]
	ds_read_b128 v[70:73], v89 offset:35312
	ds_read_b128 v[78:81], v125 offset:224
	v_add_u32_e32 v130, 0x53f0, v124
	s_waitcnt lgkmcnt(0)
	v_mfma_f32_32x32x16_bf16 v[50:65], v[70:73], v[78:81], v[50:65]
	v_mfma_f32_32x32x16_bf16 v[18:33], v[126:129], v[78:81], v[18:33]
	ds_read_b128 v[78:81], v134 offset:224
	s_waitcnt lgkmcnt(0)
	v_mfma_f32_32x32x16_bf16 v[34:49], v[70:73], v[78:81], v[34:49]
	v_add_u32_e32 v70, 2, v123
	v_cmp_gt_u32_e64 s[2:3], 16, v70
	v_add_u32_e32 v70, 0xff0, v124
	s_nop 0
	v_cndmask_b32_e64 v70, v228, v70, s[2:3]
	v_add_u32_e32 v125, v90, v70
	ds_read_b128 v[70:73], v89 offset:34768
	v_mfma_f32_32x32x16_bf16 v[2:17], v[126:129], v[78:81], v[2:17]
	ds_read_b128 v[126:129], v89 offset:34832
	ds_read_b128 v[78:81], v125
	s_waitcnt lgkmcnt(0)
	v_mfma_f32_32x32x16_bf16 v[50:65], v[126:129], v[78:81], v[50:65]
	v_mfma_f32_32x32x16_bf16 v[18:33], v[70:73], v[78:81], v[18:33]
	v_cndmask_b32_e64 v78, v228, v130, s[2:3]
	v_add_u32_e32 v142, v90, v78
	ds_read_b128 v[78:81], v142
	ds_read_b128 v[130:133], v89 offset:34864
	ds_read_b128 v[134:137], v125 offset:32
	s_waitcnt lgkmcnt(2)
	v_mfma_f32_32x32x16_bf16 v[34:49], v[126:129], v[78:81], v[34:49]
	v_mfma_f32_32x32x16_bf16 v[2:17], v[70:73], v[78:81], v[2:17]
	ds_read_b128 v[78:81], v89 offset:34800
	s_waitcnt lgkmcnt(1)
	v_mfma_f32_32x32x16_bf16 v[50:65], v[130:133], v[134:137], v[50:65]
	s_waitcnt lgkmcnt(0)
	v_mfma_f32_32x32x16_bf16 v[18:33], v[78:81], v[134:137], v[18:33]
	ds_read_b128 v[134:137], v142 offset:32
	s_waitcnt lgkmcnt(0)
	v_mfma_f32_32x32x16_bf16 v[34:49], v[130:133], v[134:137], v[34:49]
	v_mfma_f32_32x32x16_bf16 v[2:17], v[78:81], v[134:137], v[2:17]
	ds_read_b128 v[138:141], v125 offset:64
	ds_read_b128 v[200:203], v142 offset:64
	ds_read_b128 v[134:137], v89 offset:34896
	ds_read_b128 v[204:207], v125 offset:96
	ds_read_b128 v[208:211], v142 offset:96
	s_waitcnt lgkmcnt(4)
	v_mfma_f32_32x32x16_bf16 v[18:33], v[126:129], v[138:141], v[18:33]
	s_waitcnt lgkmcnt(3)
; #define MFMA(a, b, c) __builtin_amdgcn_mfma_f32_32x32x16_bf16((a), (b), (c), 0, 0, 0)
; __device__ __forceinline__ void toeplitz_item(const Params& p, int layer, int half, int c, bf16* sm, int dry, unsigned* done_ctr) {
;     ...
;       if (actv[0] && actv[1]) {
; #pragma unroll
;         for (int ks = 0; ks < 8; ++ks) {
;           const s8v a0 = *(const s8v*)(ap0 + 16 * ks), a1 = *(const s8v*)(ap0 - 32 + 16 * ks);
;           const s8v b0 = *(const s8v*)(bp0 + 16 * ks), b1 = *(const s8v*)(bp1 + 16 * ks);
;           acc[0][0] = MFMA(a0, b0, acc[0][0]);
;           acc[1][0] = MFMA(a1, b0, acc[1][0]);
;           acc[0][1] = MFMA(a0, b1, acc[0][1]);
;           acc[1][1] = MFMA(a1, b1, acc[1][1]);
;         }
	v_mfma_f32_32x32x16_bf16 v[2:17], v[126:129], v[200:203], v[2:17]
	s_waitcnt lgkmcnt(2)
	v_mfma_f32_32x32x16_bf16 v[50:65], v[134:137], v[138:141], v[50:65]
	v_mfma_f32_32x32x16_bf16 v[34:49], v[134:137], v[200:203], v[34:49]
	ds_read_b128 v[126:129], v89 offset:34928
	ds_read_b128 v[138:141], v125 offset:128
	ds_read_b128 v[200:203], v142 offset:128
	s_waitcnt lgkmcnt(4)
	v_mfma_f32_32x32x16_bf16 v[18:33], v[130:133], v[204:207], v[18:33]
	s_waitcnt lgkmcnt(3)
	v_mfma_f32_32x32x16_bf16 v[2:17], v[130:133], v[208:211], v[2:17]
	s_waitcnt lgkmcnt(2)
	v_mfma_f32_32x32x16_bf16 v[50:65], v[126:129], v[204:207], v[50:65]
	v_mfma_f32_32x32x16_bf16 v[34:49], v[126:129], v[208:211], v[34:49]
	ds_read_b128 v[130:133], v89 offset:34960
	s_waitcnt lgkmcnt(2)
	v_mfma_f32_32x32x16_bf16 v[18:33], v[134:137], v[138:141], v[18:33]
	s_waitcnt lgkmcnt(1)
	v_mfma_f32_32x32x16_bf16 v[2:17], v[134:137], v[200:203], v[2:17]
	s_waitcnt lgkmcnt(0)
	v_mfma_f32_32x32x16_bf16 v[50:65], v[130:133], v[138:141], v[50:65]
	v_mfma_f32_32x32x16_bf16 v[34:49], v[130:133], v[200:203], v[34:49]
	ds_read_b128 v[134:137], v89 offset:34992
	ds_read_b128 v[138:141], v125 offset:160
	s_waitcnt lgkmcnt(0)
	v_mfma_f32_32x32x16_bf16 v[50:65], v[134:137], v[138:141], v[50:65]
	v_mfma_f32_32x32x16_bf16 v[18:33], v[126:129], v[138:141], v[18:33]
	ds_read_b128 v[138:141], v142 offset:160
	s_waitcnt lgkmcnt(0)
	v_mfma_f32_32x32x16_bf16 v[2:17], v[126:129], v[138:141], v[2:17]
	ds_read_b128 v[126:129], v125 offset:192
	v_mfma_f32_32x32x16_bf16 v[34:49], v[134:137], v[138:141], v[34:49]
	s_waitcnt lgkmcnt(0)
	v_mfma_f32_32x32x16_bf16 v[50:65], v[66:69], v[126:129], v[50:65]
	v_mfma_f32_32x32x16_bf16 v[18:33], v[130:133], v[126:129], v[18:33]
	ds_read_b128 v[126:129], v142 offset:192
	s_waitcnt lgkmcnt(0)
	v_mfma_f32_32x32x16_bf16 v[34:49], v[66:69], v[126:129], v[34:49]
	ds_read_b128 v[66:69], v125 offset:224
	v_mfma_f32_32x32x16_bf16 v[2:17], v[130:133], v[126:129], v[2:17]
	ds_read_b128 v[126:129], v89 offset:34576
	v_add_u32_e32 v130, 0x52e0, v124
	s_waitcnt lgkmcnt(1)
	v_mfma_f32_32x32x16_bf16 v[50:65], v[74:77], v[66:69], v[50:65]
	v_mfma_f32_32x32x16_bf16 v[18:33], v[134:137], v[66:69], v[18:33]
	ds_read_b128 v[66:69], v142 offset:224
	s_waitcnt lgkmcnt(0)
	v_mfma_f32_32x32x16_bf16 v[34:49], v[74:77], v[66:69], v[34:49]
	v_mfma_f32_32x32x16_bf16 v[2:17], v[134:137], v[66:69], v[2:17]
	v_add_u32_e32 v66, 1, v123
	v_cmp_gt_u32_e64 s[2:3], 16, v66
	v_add_u32_e32 v66, 0xee0, v124
	s_nop 0
	v_cndmask_b32_e64 v66, v228, v66, s[2:3]
	v_add_u32_e32 v125, v90, v66
	ds_read_b128 v[66:69], v89 offset:34512
	ds_read_b128 v[74:77], v125
	s_waitcnt lgkmcnt(0)
	v_mfma_f32_32x32x16_bf16 v[50:65], v[126:129], v[74:77], v[50:65]
	v_mfma_f32_32x32x16_bf16 v[18:33], v[66:69], v[74:77], v[18:33]
	v_cndmask_b32_e64 v74, v228, v130, s[2:3]
	v_add_u32_e32 v142, v90, v74
	ds_read_b128 v[74:77], v142
	ds_read_b128 v[130:133], v89 offset:34608
	ds_read_b128 v[134:137], v125 offset:32
	v_cmp_gt_u32_e64 s[2:3], 16, v123
	v_add_u32_e32 v123, -4, v123
	s_waitcnt lgkmcnt(2)
	v_mfma_f32_32x32x16_bf16 v[34:49], v[126:129], v[74:77], v[34:49]
	v_mfma_f32_32x32x16_bf16 v[2:17], v[66:69], v[74:77], v[2:17]
	ds_read_b128 v[74:77], v89 offset:34544
	s_waitcnt lgkmcnt(1)
	v_mfma_f32_32x32x16_bf16 v[50:65], v[130:133], v[134:137], v[50:65]
	s_waitcnt lgkmcnt(0)
	v_mfma_f32_32x32x16_bf16 v[18:33], v[74:77], v[134:137], v[18:33]
	ds_read_b128 v[134:137], v142 offset:32
	s_waitcnt lgkmcnt(0)
	v_mfma_f32_32x32x16_bf16 v[34:49], v[130:133], v[134:137], v[34:49]
	v_mfma_f32_32x32x16_bf16 v[2:17], v[74:77], v[134:137], v[2:17]
	ds_read_b128 v[138:141], v125 offset:64
	ds_read_b128 v[200:203], v142 offset:64
	ds_read_b128 v[134:137], v89 offset:34640
	ds_read_b128 v[204:207], v125 offset:96
	ds_read_b128 v[208:211], v142 offset:96
	s_waitcnt lgkmcnt(4)
	v_mfma_f32_32x32x16_bf16 v[18:33], v[126:129], v[138:141], v[18:33]
	s_waitcnt lgkmcnt(3)
	v_mfma_f32_32x32x16_bf16 v[2:17], v[126:129], v[200:203], v[2:17]
	s_waitcnt lgkmcnt(2)
	v_mfma_f32_32x32x16_bf16 v[50:65], v[134:137], v[138:141], v[50:65]
	v_mfma_f32_32x32x16_bf16 v[34:49], v[134:137], v[200:203], v[34:49]
	ds_read_b128 v[126:129], v89 offset:34672
	ds_read_b128 v[138:141], v125 offset:128
	ds_read_b128 v[200:203], v142 offset:128
	s_waitcnt lgkmcnt(4)
	v_mfma_f32_32x32x16_bf16 v[18:33], v[130:133], v[204:207], v[18:33]
	s_waitcnt lgkmcnt(3)
	v_mfma_f32_32x32x16_bf16 v[2:17], v[130:133], v[208:211], v[2:17]
	s_waitcnt lgkmcnt(2)
	v_mfma_f32_32x32x16_bf16 v[50:65], v[126:129], v[204:207], v[50:65]
	v_mfma_f32_32x32x16_bf16 v[34:49], v[126:129], v[208:211], v[34:49]
	ds_read_b128 v[130:133], v89 offset:34704
	s_waitcnt lgkmcnt(2)
	v_mfma_f32_32x32x16_bf16 v[18:33], v[134:137], v[138:141], v[18:33]
	s_waitcnt lgkmcnt(1)
	v_mfma_f32_32x32x16_bf16 v[2:17], v[134:137], v[200:203], v[2:17]
	s_waitcnt lgkmcnt(0)
	v_mfma_f32_32x32x16_bf16 v[50:65], v[130:133], v[138:141], v[50:65]
	v_mfma_f32_32x32x16_bf16 v[34:49], v[130:133], v[200:203], v[34:49]
	ds_read_b128 v[134:137], v89 offset:34736
	ds_read_b128 v[138:141], v125 offset:160
	s_waitcnt lgkmcnt(0)
; #define MFMA(a, b, c) __builtin_amdgcn_mfma_f32_32x32x16_bf16((a), (b), (c), 0, 0, 0)
; __device__ __forceinline__ void toeplitz_item(const Params& p, int layer, int half, int c, bf16* sm, int dry, unsigned* done_ctr) {
;     ...
;       for (int ni = 0; ni < 2; ++ni) {
;         const int nlo = 32 * wn + 64 * ni;
;         actv[ni] = half ? true : !((nlo + 31 - D < 0) || (nlo - D >= 128));
;         const int n = nlo + r;
;         const int src = n - D;
;         const bool valid = half ? ((unsigned)((n & 15) - D) < 16u) : ((unsigned)src < 128u);
;         bblk[ni] = valid ? src : 128;
;       }
;       if (!actv[0] && !actv[1]) continue;
;       const int tb = 16 * (3 - Dl) + 16 + hh - rt;
;       const bf16* ap0 = sW + (aq * 83 + tb - 4 * (2 * wm)) * 8;
;       const bf16* bp0 = sU + bblk[0] * 136 + 8 * hh;
;       const bf16* bp1 = sU + bblk[1] * 136 + 8 * hh;
;       if (actv[0] && actv[1]) {
; #pragma unroll
;         for (int ks = 0; ks < 8; ++ks) {
;           const s8v a0 = *(const s8v*)(ap0 + 16 * ks), a1 = *(const s8v*)(ap0 - 32 + 16 * ks);
;           const s8v b0 = *(const s8v*)(bp0 + 16 * ks), b1 = *(const s8v*)(bp1 + 16 * ks);
;           acc[0][0] = MFMA(a0, b0, acc[0][0]);
;           acc[1][0] = MFMA(a1, b0, acc[1][0]);
;           acc[0][1] = MFMA(a0, b1, acc[0][1]);
;           acc[1][1] = MFMA(a1, b1, acc[1][1]);
;         }
	v_mfma_f32_32x32x16_bf16 v[50:65], v[134:137], v[138:141], v[50:65]
	v_mfma_f32_32x32x16_bf16 v[18:33], v[126:129], v[138:141], v[18:33]
	ds_read_b128 v[138:141], v142 offset:160
	s_waitcnt lgkmcnt(0)
	v_mfma_f32_32x32x16_bf16 v[2:17], v[126:129], v[138:141], v[2:17]
	ds_read_b128 v[126:129], v125 offset:192
	v_mfma_f32_32x32x16_bf16 v[34:49], v[134:137], v[138:141], v[34:49]
	s_waitcnt lgkmcnt(0)
	v_mfma_f32_32x32x16_bf16 v[50:65], v[70:73], v[126:129], v[50:65]
	v_mfma_f32_32x32x16_bf16 v[18:33], v[130:133], v[126:129], v[18:33]
	ds_read_b128 v[126:129], v142 offset:192
	s_waitcnt lgkmcnt(0)
	v_mfma_f32_32x32x16_bf16 v[34:49], v[70:73], v[126:129], v[34:49]
	ds_read_b128 v[70:73], v125 offset:224
	v_mfma_f32_32x32x16_bf16 v[2:17], v[130:133], v[126:129], v[2:17]
	ds_read_b128 v[126:129], v89 offset:34256
	s_waitcnt lgkmcnt(1)
	v_mfma_f32_32x32x16_bf16 v[50:65], v[78:81], v[70:73], v[50:65]
	v_mfma_f32_32x32x16_bf16 v[18:33], v[134:137], v[70:73], v[18:33]
	ds_read_b128 v[70:73], v142 offset:224
	s_waitcnt lgkmcnt(0)
	v_mfma_f32_32x32x16_bf16 v[34:49], v[78:81], v[70:73], v[34:49]
	v_add_u32_e32 v78, 0xdd0, v124
	v_cndmask_b32_e64 v78, v228, v78, s[2:3]
	v_add_u32_e32 v132, v90, v78
	ds_read_b128 v[78:81], v132
	v_add_u32_e32 v124, 0x51d0, v124
	v_mfma_f32_32x32x16_bf16 v[2:17], v[134:137], v[70:73], v[2:17]
	ds_read_b128 v[70:73], v89 offset:34320
	s_waitcnt lgkmcnt(0)
	v_mfma_f32_32x32x16_bf16 v[50:65], v[70:73], v[78:81], v[50:65]
	v_mfma_f32_32x32x16_bf16 v[18:33], v[126:129], v[78:81], v[18:33]
	v_cndmask_b32_e64 v78, v228, v124, s[2:3]
	v_add_u32_e32 v133, v90, v78
	ds_read_b128 v[78:81], v133
	s_movk_i32 s2, 0xfc00
	s_mov_b32 s3, -1
	v_lshl_add_u64 v[82:83], v[82:83], 0, s[2:3]
	v_lshl_add_u64 v[84:85], v[84:85], 0, s[2:3]
	s_waitcnt lgkmcnt(0)
	v_mfma_f32_32x32x16_bf16 v[34:49], v[70:73], v[78:81], v[34:49]
	v_lshl_add_u64 v[86:87], v[86:87], 0, s[2:3]
	v_mfma_f32_32x32x16_bf16 v[2:17], v[126:129], v[78:81], v[2:17]
	ds_read_b128 v[78:81], v89 offset:34352
	ds_read_b128 v[124:127], v132 offset:32
	ds_read_b128 v[128:131], v89 offset:34288
	s_waitcnt lgkmcnt(1)
	v_mfma_f32_32x32x16_bf16 v[50:65], v[78:81], v[124:127], v[50:65]
	s_waitcnt lgkmcnt(0)
	v_mfma_f32_32x32x16_bf16 v[18:33], v[128:131], v[124:127], v[18:33]
	ds_read_b128 v[124:127], v133 offset:32
	s_waitcnt lgkmcnt(0)
	v_mfma_f32_32x32x16_bf16 v[34:49], v[78:81], v[124:127], v[34:49]
	v_mfma_f32_32x32x16_bf16 v[2:17], v[128:131], v[124:127], v[2:17]
	ds_read_b128 v[128:131], v132 offset:64
	ds_read_b128 v[200:203], v133 offset:64
	ds_read_b128 v[124:127], v89 offset:34384
	ds_read_b128 v[204:207], v132 offset:96
	ds_read_b128 v[208:211], v133 offset:96
	s_waitcnt lgkmcnt(4)
	v_mfma_f32_32x32x16_bf16 v[18:33], v[70:73], v[128:131], v[18:33]
	s_waitcnt lgkmcnt(3)
	v_mfma_f32_32x32x16_bf16 v[2:17], v[70:73], v[200:203], v[2:17]
	s_waitcnt lgkmcnt(2)
	v_mfma_f32_32x32x16_bf16 v[50:65], v[124:127], v[128:131], v[50:65]
	v_mfma_f32_32x32x16_bf16 v[34:49], v[124:127], v[200:203], v[34:49]
	ds_read_b128 v[70:73], v89 offset:34416
	ds_read_b128 v[128:131], v132 offset:128
	ds_read_b128 v[200:203], v133 offset:128
	s_waitcnt lgkmcnt(4)
	v_mfma_f32_32x32x16_bf16 v[18:33], v[78:81], v[204:207], v[18:33]
	s_waitcnt lgkmcnt(3)
	v_mfma_f32_32x32x16_bf16 v[2:17], v[78:81], v[208:211], v[2:17]
	s_waitcnt lgkmcnt(2)
	v_mfma_f32_32x32x16_bf16 v[50:65], v[70:73], v[204:207], v[50:65]
	v_mfma_f32_32x32x16_bf16 v[34:49], v[70:73], v[208:211], v[34:49]
	ds_read_b128 v[78:81], v89 offset:34448
	s_waitcnt lgkmcnt(2)
	v_mfma_f32_32x32x16_bf16 v[18:33], v[124:127], v[128:131], v[18:33]
	s_waitcnt lgkmcnt(1)
	v_mfma_f32_32x32x16_bf16 v[2:17], v[124:127], v[200:203], v[2:17]
	s_waitcnt lgkmcnt(0)
	v_mfma_f32_32x32x16_bf16 v[50:65], v[78:81], v[128:131], v[50:65]
	v_mfma_f32_32x32x16_bf16 v[34:49], v[78:81], v[200:203], v[34:49]
	ds_read_b128 v[124:127], v89 offset:34480
	ds_read_b128 v[128:131], v132 offset:160
	s_waitcnt lgkmcnt(0)
	v_mfma_f32_32x32x16_bf16 v[50:65], v[124:127], v[128:131], v[50:65]
	v_mfma_f32_32x32x16_bf16 v[18:33], v[70:73], v[128:131], v[18:33]
	ds_read_b128 v[128:131], v133 offset:160
	s_waitcnt lgkmcnt(0)
	v_mfma_f32_32x32x16_bf16 v[2:17], v[70:73], v[128:131], v[2:17]
	ds_read_b128 v[70:73], v132 offset:192
	v_mfma_f32_32x32x16_bf16 v[34:49], v[124:127], v[128:131], v[34:49]
	s_waitcnt lgkmcnt(0)
	v_mfma_f32_32x32x16_bf16 v[50:65], v[66:69], v[70:73], v[50:65]
	v_mfma_f32_32x32x16_bf16 v[18:33], v[78:81], v[70:73], v[18:33]
	ds_read_b128 v[70:73], v133 offset:192
	s_waitcnt lgkmcnt(0)
	v_mfma_f32_32x32x16_bf16 v[34:49], v[66:69], v[70:73], v[34:49]
	ds_read_b128 v[66:69], v132 offset:224
	v_mfma_f32_32x32x16_bf16 v[2:17], v[78:81], v[70:73], v[2:17]
	s_waitcnt lgkmcnt(0)
	v_mfma_f32_32x32x16_bf16 v[50:65], v[74:77], v[66:69], v[50:65]
	v_mfma_f32_32x32x16_bf16 v[18:33], v[124:127], v[66:69], v[18:33]
	ds_read_b128 v[66:69], v133 offset:224
	s_waitcnt lgkmcnt(0)
	v_mfma_f32_32x32x16_bf16 v[34:49], v[74:77], v[66:69], v[34:49]
	v_mfma_f32_32x32x16_bf16 v[2:17], v[124:127], v[66:69], v[2:17]
	s_cbranch_scc1 .LBB0_1205

; #define MFMA(a, b, c) __builtin_amdgcn_mfma_f32_32x32x16_bf16((a), (b), (c), 0, 0, 0)
; __device__ __forceinline__ void toeplitz_item(const Params& p, int layer, int half, int c, bf16* sm, int dry, unsigned* done_ctr) {
;     ...
;       if (actv[0] && actv[1]) {
; #pragma unroll
;         for (int ks = 0; ks < 8; ++ks) {
;           const s8v a0 = *(const s8v*)(ap0 + 16 * ks), a1 = *(const s8v*)(ap0 - 32 + 16 * ks);
;           const s8v b0 = *(const s8v*)(bp0 + 16 * ks), b1 = *(const s8v*)(bp1 + 16 * ks);
;           acc[0][0] = MFMA(a0, b0, acc[0][0]);
;           acc[1][0] = MFMA(a1, b0, acc[1][0]);
;           acc[0][1] = MFMA(a0, b1, acc[0][1]);
;           acc[1][1] = MFMA(a1, b1, acc[1][1]);
;         }
.LBB0_1429:
	s_andn2_saveexec_b64 s[94:95], s[20:21]
	s_cbranch_execz .LBB0_1431
	v_add_u32_e32 v14, v106, v14
	s_waitcnt lgkmcnt(0)
	ds_read_b128 v[6:9], v14
	v_add_u32_e32 v15, v106, v15
	s_waitcnt lgkmcnt(0)
	v_mfma_f32_32x32x16_bf16 v[64:79], v[2:5], v[6:9], v[64:79]
	v_mfma_f32_32x32x16_bf16 v[32:47], v[84:87], v[6:9], v[32:47]
	ds_read_b128 v[6:9], v15
	s_waitcnt lgkmcnt(0)
	v_mfma_f32_32x32x16_bf16 v[48:63], v[2:5], v[6:9], v[48:63]
	v_mfma_f32_32x32x16_bf16 v[16:31], v[84:87], v[6:9], v[16:31]
	ds_read_b128 v[6:9], v108 offset:35120
	ds_read_b128 v[10:13], v14 offset:32
	ds_read_b128 v[80:83], v108 offset:35056
	s_waitcnt lgkmcnt(1)
	v_mfma_f32_32x32x16_bf16 v[64:79], v[6:9], v[10:13], v[64:79]
	s_waitcnt lgkmcnt(0)
	v_mfma_f32_32x32x16_bf16 v[32:47], v[80:83], v[10:13], v[32:47]
	ds_read_b128 v[10:13], v15 offset:32
	s_waitcnt lgkmcnt(0)
	v_mfma_f32_32x32x16_bf16 v[48:63], v[6:9], v[10:13], v[48:63]
	v_mfma_f32_32x32x16_bf16 v[16:31], v[80:83], v[10:13], v[16:31]
	ds_read_b128 v[80:83], v14 offset:64
	ds_read_b128 v[200:203], v15 offset:64
	ds_read_b128 v[10:13], v108 offset:35152
	ds_read_b128 v[204:207], v14 offset:96
	ds_read_b128 v[208:211], v15 offset:96
	s_waitcnt lgkmcnt(4)
	v_mfma_f32_32x32x16_bf16 v[32:47], v[2:5], v[80:83], v[32:47]
	s_waitcnt lgkmcnt(3)
	v_mfma_f32_32x32x16_bf16 v[16:31], v[2:5], v[200:203], v[16:31]
	s_waitcnt lgkmcnt(2)
	v_mfma_f32_32x32x16_bf16 v[64:79], v[10:13], v[80:83], v[64:79]
	v_mfma_f32_32x32x16_bf16 v[48:63], v[10:13], v[200:203], v[48:63]
	ds_read_b128 v[2:5], v108 offset:35184
	ds_read_b128 v[80:83], v14 offset:128
	ds_read_b128 v[200:203], v15 offset:128
	s_waitcnt lgkmcnt(4)
	v_mfma_f32_32x32x16_bf16 v[32:47], v[6:9], v[204:207], v[32:47]
	s_waitcnt lgkmcnt(3)
	v_mfma_f32_32x32x16_bf16 v[16:31], v[6:9], v[208:211], v[16:31]
	s_waitcnt lgkmcnt(2)
	v_mfma_f32_32x32x16_bf16 v[64:79], v[2:5], v[204:207], v[64:79]
	v_mfma_f32_32x32x16_bf16 v[48:63], v[2:5], v[208:211], v[48:63]
	ds_read_b128 v[6:9], v108 offset:35216
	ds_read_b128 v[204:207], v14 offset:160
	ds_read_b128 v[208:211], v15 offset:160
	s_waitcnt lgkmcnt(4)
	v_mfma_f32_32x32x16_bf16 v[32:47], v[10:13], v[80:83], v[32:47]
	s_waitcnt lgkmcnt(3)
	v_mfma_f32_32x32x16_bf16 v[16:31], v[10:13], v[200:203], v[16:31]
	s_waitcnt lgkmcnt(2)
	v_mfma_f32_32x32x16_bf16 v[64:79], v[6:9], v[80:83], v[64:79]
	v_mfma_f32_32x32x16_bf16 v[48:63], v[6:9], v[200:203], v[48:63]
	ds_read_b128 v[10:13], v108 offset:35248
	s_waitcnt lgkmcnt(2)
	v_mfma_f32_32x32x16_bf16 v[32:47], v[2:5], v[204:207], v[32:47]
	s_waitcnt lgkmcnt(1)
	v_mfma_f32_32x32x16_bf16 v[16:31], v[2:5], v[208:211], v[16:31]
	s_waitcnt lgkmcnt(0)
	v_mfma_f32_32x32x16_bf16 v[64:79], v[10:13], v[204:207], v[64:79]
	v_mfma_f32_32x32x16_bf16 v[48:63], v[10:13], v[208:211], v[48:63]
	ds_read_b128 v[2:5], v108 offset:35280
	ds_read_b128 v[80:83], v14 offset:192
	s_waitcnt lgkmcnt(0)
	v_mfma_f32_32x32x16_bf16 v[64:79], v[2:5], v[80:83], v[64:79]
	v_mfma_f32_32x32x16_bf16 v[32:47], v[6:9], v[80:83], v[32:47]
	ds_read_b128 v[80:83], v15 offset:192
	s_waitcnt lgkmcnt(0)
	v_mfma_f32_32x32x16_bf16 v[48:63], v[2:5], v[80:83], v[48:63]
	v_mfma_f32_32x32x16_bf16 v[16:31], v[6:9], v[80:83], v[16:31]
	ds_read_b128 v[2:5], v108 offset:35312
	ds_read_b128 v[6:9], v14 offset:224
	s_waitcnt lgkmcnt(0)
	v_mfma_f32_32x32x16_bf16 v[64:79], v[2:5], v[6:9], v[64:79]
	v_mfma_f32_32x32x16_bf16 v[32:47], v[10:13], v[6:9], v[32:47]
	ds_read_b128 v[6:9], v15 offset:224
	s_waitcnt lgkmcnt(0)
	v_mfma_f32_32x32x16_bf16 v[48:63], v[2:5], v[6:9], v[48:63]
	v_mfma_f32_32x32x16_bf16 v[16:31], v[10:13], v[6:9], v[16:31]

; #define MFMA(a, b, c) __builtin_amdgcn_mfma_f32_32x32x16_bf16((a), (b), (c), 0, 0, 0)
; __device__ __forceinline__ void toeplitz_item(const Params& p, int layer, int half, int c, bf16* sm, int dry, unsigned* done_ctr) {
;     ...
;       if (actv[0] && actv[1]) {
; #pragma unroll
;         for (int ks = 0; ks < 8; ++ks) {
;           const s8v a0 = *(const s8v*)(ap0 + 16 * ks), a1 = *(const s8v*)(ap0 - 32 + 16 * ks);
;           const s8v b0 = *(const s8v*)(bp0 + 16 * ks), b1 = *(const s8v*)(bp1 + 16 * ks);
;           acc[0][0] = MFMA(a0, b0, acc[0][0]);
;           acc[1][0] = MFMA(a1, b0, acc[1][0]);
;           acc[0][1] = MFMA(a0, b1, acc[0][1]);
;           acc[1][1] = MFMA(a1, b1, acc[1][1]);
;         }
.LBB0_1439:
	s_andn2_saveexec_b64 s[20:21], s[20:21]
	s_cbranch_execz .LBB0_1441
	v_add_u32_e32 v14, v106, v14
	s_waitcnt lgkmcnt(0)
	ds_read_b128 v[6:9], v14
	v_add_u32_e32 v15, v106, v15
	s_waitcnt lgkmcnt(0)
	v_mfma_f32_32x32x16_bf16 v[64:79], v[2:5], v[6:9], v[64:79]
	v_mfma_f32_32x32x16_bf16 v[32:47], v[84:87], v[6:9], v[32:47]
	ds_read_b128 v[6:9], v15
	s_waitcnt lgkmcnt(0)
	v_mfma_f32_32x32x16_bf16 v[48:63], v[2:5], v[6:9], v[48:63]
	v_mfma_f32_32x32x16_bf16 v[16:31], v[84:87], v[6:9], v[16:31]
	ds_read_b128 v[6:9], v108 offset:34864
	ds_read_b128 v[10:13], v14 offset:32
	ds_read_b128 v[80:83], v108 offset:34800
	s_waitcnt lgkmcnt(1)
	v_mfma_f32_32x32x16_bf16 v[64:79], v[6:9], v[10:13], v[64:79]
	s_waitcnt lgkmcnt(0)
	v_mfma_f32_32x32x16_bf16 v[32:47], v[80:83], v[10:13], v[32:47]
	ds_read_b128 v[10:13], v15 offset:32
	s_waitcnt lgkmcnt(0)
	v_mfma_f32_32x32x16_bf16 v[48:63], v[6:9], v[10:13], v[48:63]
	v_mfma_f32_32x32x16_bf16 v[16:31], v[80:83], v[10:13], v[16:31]
	ds_read_b128 v[80:83], v14 offset:64
	ds_read_b128 v[200:203], v15 offset:64
	ds_read_b128 v[10:13], v108 offset:34896
	ds_read_b128 v[204:207], v14 offset:96
	ds_read_b128 v[208:211], v15 offset:96
	s_waitcnt lgkmcnt(4)
	v_mfma_f32_32x32x16_bf16 v[32:47], v[2:5], v[80:83], v[32:47]
	s_waitcnt lgkmcnt(3)
	v_mfma_f32_32x32x16_bf16 v[16:31], v[2:5], v[200:203], v[16:31]
	s_waitcnt lgkmcnt(2)
	v_mfma_f32_32x32x16_bf16 v[64:79], v[10:13], v[80:83], v[64:79]
	v_mfma_f32_32x32x16_bf16 v[48:63], v[10:13], v[200:203], v[48:63]
	ds_read_b128 v[2:5], v108 offset:34928
	ds_read_b128 v[80:83], v14 offset:128
	ds_read_b128 v[200:203], v15 offset:128
	s_waitcnt lgkmcnt(4)
	v_mfma_f32_32x32x16_bf16 v[32:47], v[6:9], v[204:207], v[32:47]
	s_waitcnt lgkmcnt(3)
	v_mfma_f32_32x32x16_bf16 v[16:31], v[6:9], v[208:211], v[16:31]
	s_waitcnt lgkmcnt(2)
	v_mfma_f32_32x32x16_bf16 v[64:79], v[2:5], v[204:207], v[64:79]
	v_mfma_f32_32x32x16_bf16 v[48:63], v[2:5], v[208:211], v[48:63]
	ds_read_b128 v[6:9], v108 offset:34960
	ds_read_b128 v[204:207], v14 offset:160
	ds_read_b128 v[208:211], v15 offset:160
	s_waitcnt lgkmcnt(4)
	v_mfma_f32_32x32x16_bf16 v[32:47], v[10:13], v[80:83], v[32:47]
	s_waitcnt lgkmcnt(3)
	v_mfma_f32_32x32x16_bf16 v[16:31], v[10:13], v[200:203], v[16:31]
	s_waitcnt lgkmcnt(2)
	v_mfma_f32_32x32x16_bf16 v[64:79], v[6:9], v[80:83], v[64:79]
	v_mfma_f32_32x32x16_bf16 v[48:63], v[6:9], v[200:203], v[48:63]
	ds_read_b128 v[10:13], v108 offset:34992
	s_waitcnt lgkmcnt(2)
	v_mfma_f32_32x32x16_bf16 v[32:47], v[2:5], v[204:207], v[32:47]
	s_waitcnt lgkmcnt(1)
	v_mfma_f32_32x32x16_bf16 v[16:31], v[2:5], v[208:211], v[16:31]
	s_waitcnt lgkmcnt(0)
	v_mfma_f32_32x32x16_bf16 v[64:79], v[10:13], v[204:207], v[64:79]
	v_mfma_f32_32x32x16_bf16 v[48:63], v[10:13], v[208:211], v[48:63]
	ds_read_b128 v[2:5], v108 offset:35024
	ds_read_b128 v[80:83], v14 offset:192
	s_waitcnt lgkmcnt(0)
	v_mfma_f32_32x32x16_bf16 v[64:79], v[2:5], v[80:83], v[64:79]
	v_mfma_f32_32x32x16_bf16 v[32:47], v[6:9], v[80:83], v[32:47]
	ds_read_b128 v[80:83], v15 offset:192
	s_waitcnt lgkmcnt(0)
	v_mfma_f32_32x32x16_bf16 v[48:63], v[2:5], v[80:83], v[48:63]
	v_mfma_f32_32x32x16_bf16 v[16:31], v[6:9], v[80:83], v[16:31]
	ds_read_b128 v[2:5], v108 offset:35056
	ds_read_b128 v[6:9], v14 offset:224
	s_waitcnt lgkmcnt(0)
	v_mfma_f32_32x32x16_bf16 v[64:79], v[2:5], v[6:9], v[64:79]
	v_mfma_f32_32x32x16_bf16 v[32:47], v[10:13], v[6:9], v[32:47]
	ds_read_b128 v[6:9], v15 offset:224
	s_waitcnt lgkmcnt(0)
	v_mfma_f32_32x32x16_bf16 v[48:63], v[2:5], v[6:9], v[48:63]
	v_mfma_f32_32x32x16_bf16 v[16:31], v[10:13], v[6:9], v[16:31]

; #define MFMA(a, b, c) __builtin_amdgcn_mfma_f32_32x32x16_bf16((a), (b), (c), 0, 0, 0)
; __device__ __forceinline__ void toeplitz_item(const Params& p, int layer, int half, int c, bf16* sm, int dry, unsigned* done_ctr) {
;     ...
;       if (actv[0] && actv[1]) {
; #pragma unroll
;         for (int ks = 0; ks < 8; ++ks) {
;           const s8v a0 = *(const s8v*)(ap0 + 16 * ks), a1 = *(const s8v*)(ap0 - 32 + 16 * ks);
;           const s8v b0 = *(const s8v*)(bp0 + 16 * ks), b1 = *(const s8v*)(bp1 + 16 * ks);
;           acc[0][0] = MFMA(a0, b0, acc[0][0]);
;           acc[1][0] = MFMA(a1, b0, acc[1][0]);
;           acc[0][1] = MFMA(a0, b1, acc[0][1]);
;           acc[1][1] = MFMA(a1, b1, acc[1][1]);
;         }
.LBB0_1449:
	s_andn2_saveexec_b64 s[20:21], s[20:21]
	s_cbranch_execz .LBB0_1451
	v_add_u32_e32 v14, v106, v14
	s_waitcnt lgkmcnt(0)
	ds_read_b128 v[6:9], v14
	v_add_u32_e32 v15, v106, v15
	s_waitcnt lgkmcnt(0)
	v_mfma_f32_32x32x16_bf16 v[64:79], v[2:5], v[6:9], v[64:79]
	v_mfma_f32_32x32x16_bf16 v[32:47], v[84:87], v[6:9], v[32:47]
	ds_read_b128 v[6:9], v15
	s_waitcnt lgkmcnt(0)
	v_mfma_f32_32x32x16_bf16 v[48:63], v[2:5], v[6:9], v[48:63]
	v_mfma_f32_32x32x16_bf16 v[16:31], v[84:87], v[6:9], v[16:31]
	ds_read_b128 v[6:9], v108 offset:34608
	ds_read_b128 v[10:13], v14 offset:32
	ds_read_b128 v[80:83], v108 offset:34544
	s_waitcnt lgkmcnt(1)
	v_mfma_f32_32x32x16_bf16 v[64:79], v[6:9], v[10:13], v[64:79]
	s_waitcnt lgkmcnt(0)
	v_mfma_f32_32x32x16_bf16 v[32:47], v[80:83], v[10:13], v[32:47]
	ds_read_b128 v[10:13], v15 offset:32
	s_waitcnt lgkmcnt(0)
	v_mfma_f32_32x32x16_bf16 v[48:63], v[6:9], v[10:13], v[48:63]
	v_mfma_f32_32x32x16_bf16 v[16:31], v[80:83], v[10:13], v[16:31]
	ds_read_b128 v[80:83], v14 offset:64
	ds_read_b128 v[200:203], v15 offset:64
	ds_read_b128 v[10:13], v108 offset:34640
	ds_read_b128 v[204:207], v14 offset:96
	ds_read_b128 v[208:211], v15 offset:96
	s_waitcnt lgkmcnt(4)
	v_mfma_f32_32x32x16_bf16 v[32:47], v[2:5], v[80:83], v[32:47]
	s_waitcnt lgkmcnt(3)
	v_mfma_f32_32x32x16_bf16 v[16:31], v[2:5], v[200:203], v[16:31]
	s_waitcnt lgkmcnt(2)
	v_mfma_f32_32x32x16_bf16 v[64:79], v[10:13], v[80:83], v[64:79]
	v_mfma_f32_32x32x16_bf16 v[48:63], v[10:13], v[200:203], v[48:63]
	ds_read_b128 v[2:5], v108 offset:34672
	ds_read_b128 v[80:83], v14 offset:128
	ds_read_b128 v[200:203], v15 offset:128
	s_waitcnt lgkmcnt(4)
	v_mfma_f32_32x32x16_bf16 v[32:47], v[6:9], v[204:207], v[32:47]
	s_waitcnt lgkmcnt(3)
	v_mfma_f32_32x32x16_bf16 v[16:31], v[6:9], v[208:211], v[16:31]
	s_waitcnt lgkmcnt(2)
	v_mfma_f32_32x32x16_bf16 v[64:79], v[2:5], v[204:207], v[64:79]
	v_mfma_f32_32x32x16_bf16 v[48:63], v[2:5], v[208:211], v[48:63]
	ds_read_b128 v[6:9], v108 offset:34704
	ds_read_b128 v[204:207], v14 offset:160
	ds_read_b128 v[208:211], v15 offset:160
	s_waitcnt lgkmcnt(4)
	v_mfma_f32_32x32x16_bf16 v[32:47], v[10:13], v[80:83], v[32:47]
	s_waitcnt lgkmcnt(3)
	v_mfma_f32_32x32x16_bf16 v[16:31], v[10:13], v[200:203], v[16:31]
	s_waitcnt lgkmcnt(2)
	v_mfma_f32_32x32x16_bf16 v[64:79], v[6:9], v[80:83], v[64:79]
	v_mfma_f32_32x32x16_bf16 v[48:63], v[6:9], v[200:203], v[48:63]
	ds_read_b128 v[10:13], v108 offset:34736
	s_waitcnt lgkmcnt(2)
	v_mfma_f32_32x32x16_bf16 v[32:47], v[2:5], v[204:207], v[32:47]
	s_waitcnt lgkmcnt(1)
	v_mfma_f32_32x32x16_bf16 v[16:31], v[2:5], v[208:211], v[16:31]
	s_waitcnt lgkmcnt(0)
	v_mfma_f32_32x32x16_bf16 v[64:79], v[10:13], v[204:207], v[64:79]
	v_mfma_f32_32x32x16_bf16 v[48:63], v[10:13], v[208:211], v[48:63]
	ds_read_b128 v[2:5], v108 offset:34768
	ds_read_b128 v[80:83], v14 offset:192
	s_waitcnt lgkmcnt(0)
	v_mfma_f32_32x32x16_bf16 v[64:79], v[2:5], v[80:83], v[64:79]
	v_mfma_f32_32x32x16_bf16 v[32:47], v[6:9], v[80:83], v[32:47]
	ds_read_b128 v[80:83], v15 offset:192
	s_waitcnt lgkmcnt(0)
	v_mfma_f32_32x32x16_bf16 v[48:63], v[2:5], v[80:83], v[48:63]
	v_mfma_f32_32x32x16_bf16 v[16:31], v[6:9], v[80:83], v[16:31]
	ds_read_b128 v[2:5], v108 offset:34800
	ds_read_b128 v[6:9], v14 offset:224
	s_waitcnt lgkmcnt(0)
	v_mfma_f32_32x32x16_bf16 v[64:79], v[2:5], v[6:9], v[64:79]
	v_mfma_f32_32x32x16_bf16 v[32:47], v[10:13], v[6:9], v[32:47]
	ds_read_b128 v[6:9], v15 offset:224
	s_waitcnt lgkmcnt(0)
	v_mfma_f32_32x32x16_bf16 v[48:63], v[2:5], v[6:9], v[48:63]
	v_mfma_f32_32x32x16_bf16 v[16:31], v[10:13], v[6:9], v[16:31]

; #define MFMA(a, b, c) __builtin_amdgcn_mfma_f32_32x32x16_bf16((a), (b), (c), 0, 0, 0)
; __device__ __forceinline__ void toeplitz_item(const Params& p, int layer, int half, int c, bf16* sm, int dry, unsigned* done_ctr) {
;     ...
;       if (actv[0] && actv[1]) {
; #pragma unroll
;         for (int ks = 0; ks < 8; ++ks) {
;           const s8v a0 = *(const s8v*)(ap0 + 16 * ks), a1 = *(const s8v*)(ap0 - 32 + 16 * ks);
;           const s8v b0 = *(const s8v*)(bp0 + 16 * ks), b1 = *(const s8v*)(bp1 + 16 * ks);
;           acc[0][0] = MFMA(a0, b0, acc[0][0]);
;           acc[1][0] = MFMA(a1, b0, acc[1][0]);
;           acc[0][1] = MFMA(a0, b1, acc[0][1]);
;           acc[1][1] = MFMA(a1, b1, acc[1][1]);
;         }
.LBB0_1459:
	s_andn2_saveexec_b64 s[20:21], s[20:21]
	s_cbranch_execz .LBB0_1369
	v_add_u32_e32 v0, v106, v0
	s_waitcnt lgkmcnt(0)
	ds_read_b128 v[6:9], v0
	v_add_u32_e32 v14, v106, v14
	s_waitcnt lgkmcnt(0)
	v_mfma_f32_32x32x16_bf16 v[64:79], v[2:5], v[6:9], v[64:79]
	v_mfma_f32_32x32x16_bf16 v[32:47], v[84:87], v[6:9], v[32:47]
	ds_read_b128 v[6:9], v14
	s_waitcnt lgkmcnt(0)
	v_mfma_f32_32x32x16_bf16 v[48:63], v[2:5], v[6:9], v[48:63]
	v_mfma_f32_32x32x16_bf16 v[16:31], v[84:87], v[6:9], v[16:31]
	ds_read_b128 v[6:9], v108 offset:34352
	ds_read_b128 v[10:13], v0 offset:32
	ds_read_b128 v[80:83], v108 offset:34288
	s_waitcnt lgkmcnt(1)
	v_mfma_f32_32x32x16_bf16 v[64:79], v[6:9], v[10:13], v[64:79]
	s_waitcnt lgkmcnt(0)
	v_mfma_f32_32x32x16_bf16 v[32:47], v[80:83], v[10:13], v[32:47]
	ds_read_b128 v[10:13], v14 offset:32
	s_waitcnt lgkmcnt(0)
	v_mfma_f32_32x32x16_bf16 v[48:63], v[6:9], v[10:13], v[48:63]
	v_mfma_f32_32x32x16_bf16 v[16:31], v[80:83], v[10:13], v[16:31]
	ds_read_b128 v[80:83], v0 offset:64
	ds_read_b128 v[200:203], v14 offset:64
	ds_read_b128 v[10:13], v108 offset:34384
	ds_read_b128 v[204:207], v0 offset:96
	ds_read_b128 v[208:211], v14 offset:96
	s_waitcnt lgkmcnt(4)
	v_mfma_f32_32x32x16_bf16 v[32:47], v[2:5], v[80:83], v[32:47]
	s_waitcnt lgkmcnt(3)
	v_mfma_f32_32x32x16_bf16 v[16:31], v[2:5], v[200:203], v[16:31]
	s_waitcnt lgkmcnt(2)
	v_mfma_f32_32x32x16_bf16 v[64:79], v[10:13], v[80:83], v[64:79]
	v_mfma_f32_32x32x16_bf16 v[48:63], v[10:13], v[200:203], v[48:63]
	ds_read_b128 v[2:5], v108 offset:34416
	ds_read_b128 v[80:83], v0 offset:128
	ds_read_b128 v[200:203], v14 offset:128
	s_waitcnt lgkmcnt(4)
	v_mfma_f32_32x32x16_bf16 v[32:47], v[6:9], v[204:207], v[32:47]
	s_waitcnt lgkmcnt(3)
	v_mfma_f32_32x32x16_bf16 v[16:31], v[6:9], v[208:211], v[16:31]
	s_waitcnt lgkmcnt(2)
	v_mfma_f32_32x32x16_bf16 v[64:79], v[2:5], v[204:207], v[64:79]
	v_mfma_f32_32x32x16_bf16 v[48:63], v[2:5], v[208:211], v[48:63]
	ds_read_b128 v[6:9], v108 offset:34448
	ds_read_b128 v[204:207], v0 offset:160
	ds_read_b128 v[208:211], v14 offset:160
	s_waitcnt lgkmcnt(4)
	v_mfma_f32_32x32x16_bf16 v[32:47], v[10:13], v[80:83], v[32:47]
	s_waitcnt lgkmcnt(3)
	v_mfma_f32_32x32x16_bf16 v[16:31], v[10:13], v[200:203], v[16:31]
	s_waitcnt lgkmcnt(2)
	v_mfma_f32_32x32x16_bf16 v[64:79], v[6:9], v[80:83], v[64:79]
	v_mfma_f32_32x32x16_bf16 v[48:63], v[6:9], v[200:203], v[48:63]
	ds_read_b128 v[10:13], v108 offset:34480
	s_waitcnt lgkmcnt(2)
	v_mfma_f32_32x32x16_bf16 v[32:47], v[2:5], v[204:207], v[32:47]
	s_waitcnt lgkmcnt(1)
	v_mfma_f32_32x32x16_bf16 v[16:31], v[2:5], v[208:211], v[16:31]
	s_waitcnt lgkmcnt(0)
	v_mfma_f32_32x32x16_bf16 v[64:79], v[10:13], v[204:207], v[64:79]
	v_mfma_f32_32x32x16_bf16 v[48:63], v[10:13], v[208:211], v[48:63]
	ds_read_b128 v[2:5], v108 offset:34512
	ds_read_b128 v[80:83], v0 offset:192
	s_waitcnt lgkmcnt(0)
	v_mfma_f32_32x32x16_bf16 v[64:79], v[2:5], v[80:83], v[64:79]
	v_mfma_f32_32x32x16_bf16 v[32:47], v[6:9], v[80:83], v[32:47]
	ds_read_b128 v[80:83], v14 offset:192
	s_waitcnt lgkmcnt(0)
	v_mfma_f32_32x32x16_bf16 v[48:63], v[2:5], v[80:83], v[48:63]
	v_mfma_f32_32x32x16_bf16 v[16:31], v[6:9], v[80:83], v[16:31]
	ds_read_b128 v[2:5], v108 offset:34544
	ds_read_b128 v[6:9], v0 offset:224
	s_waitcnt lgkmcnt(0)
	v_mfma_f32_32x32x16_bf16 v[64:79], v[2:5], v[6:9], v[64:79]
	v_mfma_f32_32x32x16_bf16 v[32:47], v[10:13], v[6:9], v[32:47]
	ds_read_b128 v[6:9], v14 offset:224
	s_waitcnt lgkmcnt(0)
	v_mfma_f32_32x32x16_bf16 v[48:63], v[2:5], v[6:9], v[48:63]
	v_mfma_f32_32x32x16_bf16 v[16:31], v[10:13], v[6:9], v[16:31]
	s_branch .LBB0_1369
